# attention PV: the next V-fragment read is issued behind the four cvt_pk so it supplies the VALU->MFMA wait state (5 fewer s_nop per two tiles)
# baseline (speedup 1.0000x reference)
; DI void attn_item(const Params& p, int item, char* smem) {
;     ...
;     float ps = 0.f;
; #pragma unroll
;     for (int i = 0; i < 16; ++i) { p0[i] = __builtin_amdgcn_exp2f(p0[i] - mrun); ps += p0[i]; }
; #pragma unroll
;     for (int i = 0; i < 16; ++i) { p1[i] = __builtin_amdgcn_exp2f(p1[i] - mrun); ps += p1[i]; }
;     lrun += ps;
;     pv_step(o0, o1, Vc, r32, 0 + hi * 4, pack8<0>(p0));
;     pv_step(o0, o1, Vc, r32, 16 + hi * 4, pack8<8>(p0));
;     pv_step(o0, o1, Vc, r32, 32 + hi * 4, pack8<0>(p1));
;     pv_step(o0, o1, Vc, r32, 48 + hi * 4, pack8<8>(p1));
;   };
;   __syncthreads();
;   gload(a, 0); lstore(a, 0);
;   gload(a, 1);
;   __syncthreads();
;   for (int kt = 0; kt < nkt; kt += 2) {
;     if (kt + 2 < nkt) gload(b, kt + 2);
;     tile_compute(0);
;     lstore(a, 1);
;     __syncthreads();
;     if (kt + 3 < nkt) gload(a, kt + 3);
.LBB0_533:
	v_add_f32_e32 v157, v157, v0
	ds_read2_b64 v[212:215], v224 offset0:32 offset1:34
	ds_read2_b64 v[216:219], v225 offset1:2
	v_cvt_pk_bf16_f32 v220, v168, v169
	v_cvt_pk_bf16_f32 v221, v170, v171
	v_cvt_pk_bf16_f32 v222, v172, v173
	v_cvt_pk_bf16_f32 v223, v174, v175
	s_add_i32 s12, s12, 3
	s_waitcnt lgkmcnt(1)
	v_mfma_f32_32x32x16_bf16 v[16:31], v[212:215], v[220:223], v[16:31]
	ds_read2_b64 v[212:215], v224 offset0:36 offset1:38
	s_waitcnt lgkmcnt(1)
	v_mfma_f32_32x32x16_bf16 v[32:47], v[216:219], v[220:223], v[32:47]
	v_cvt_pk_bf16_f32 v220, v176, v177
	v_cvt_pk_bf16_f32 v221, v178, v179
	v_cvt_pk_bf16_f32 v222, v180, v181
	v_cvt_pk_bf16_f32 v223, v182, v183
	ds_read2_b64 v[216:219], v225 offset0:4 offset1:6
	s_waitcnt lgkmcnt(1)
	v_mfma_f32_32x32x16_bf16 v[16:31], v[212:215], v[220:223], v[16:31]
	ds_read2_b64 v[212:215], v224 offset0:40 offset1:42
	s_waitcnt lgkmcnt(1)
	v_mfma_f32_32x32x16_bf16 v[32:47], v[216:219], v[220:223], v[32:47]
	v_cvt_pk_bf16_f32 v220, v184, v185
	v_cvt_pk_bf16_f32 v221, v186, v187
	v_cvt_pk_bf16_f32 v222, v188, v189
	v_cvt_pk_bf16_f32 v223, v190, v191
	ds_read2_b64 v[216:219], v225 offset0:8 offset1:10
	s_waitcnt lgkmcnt(1)
	v_mfma_f32_32x32x16_bf16 v[16:31], v[212:215], v[220:223], v[16:31]
	ds_read2_b64 v[212:215], v224 offset0:44 offset1:46
	s_waitcnt lgkmcnt(1)
	v_mfma_f32_32x32x16_bf16 v[32:47], v[216:219], v[220:223], v[32:47]
	ds_read2_b64 v[216:219], v225 offset0:12 offset1:14
	s_waitcnt vmcnt(0)
	ds_write_b128 v150, v[104:107] offset:13312
	ds_write_b128 v151, v[108:111] offset:13312
	ds_write_b128 v152, v[112:115] offset:13312
	v_cvt_pk_bf16_f32 v220, v158, v159
	v_cvt_pk_bf16_f32 v221, v160, v161
	v_cvt_pk_bf16_f32 v222, v164, v165
	v_cvt_pk_bf16_f32 v223, v166, v167
	s_cmp_ge_u32 s12, s10
	s_waitcnt lgkmcnt(4)
	v_mfma_f32_32x32x16_bf16 v[16:31], v[212:215], v[220:223], v[16:31]
	s_waitcnt lgkmcnt(3)
	v_mfma_f32_32x32x16_bf16 v[32:47], v[216:219], v[220:223], v[32:47]
	ds_write2_b64 v226, v[116:117], v[118:119] offset1:1
	ds_write2_b64 v227, v[120:121], v[122:123] offset1:1
	s_waitcnt lgkmcnt(0)
	s_barrier
	s_cbranch_scc1 .LBB0_535
	global_load_dwordx4 v[104:107], v146, s[24:25]
	global_load_dwordx4 v[108:111], v144, s[24:25]
	global_load_dwordx4 v[112:115], v142, s[24:25]
	global_load_dwordx4 v[116:119], v140, s[26:27] offset:384
	global_load_dwordx4 v[120:123], v140, s[28:29] offset:384

; DI void attn_item(const Params& p, int item, char* smem) {
;     ...
;     pv_step(o0, o1, Vc, r32, 0 + hi * 4, pack8<0>(p0));
;     pv_step(o0, o1, Vc, r32, 16 + hi * 4, pack8<8>(p0));
;     pv_step(o0, o1, Vc, r32, 32 + hi * 4, pack8<0>(p1));
;     pv_step(o0, o1, Vc, r32, 48 + hi * 4, pack8<8>(p1));
;   };
;   __syncthreads();
;   gload(a, 0); lstore(a, 0);
;   gload(a, 1);
;   __syncthreads();
;   for (int kt = 0; kt < nkt; kt += 2) {
;     if (kt + 2 < nkt) gload(b, kt + 2);
;     tile_compute(0);
;     lstore(a, 1);
;     __syncthreads();
;     if (kt + 3 < nkt) gload(a, kt + 3);
;     tile_compute(1);
;     if (kt + 2 < nkt) lstore(b, 0);
;     __syncthreads();
.LBB0_537:
	v_add_f32_e32 v157, v157, v0
	ds_read2_b64 v[212:215], v228 offset0:64 offset1:66
	ds_read2_b64 v[216:219], v229 offset0:96 offset1:98
	v_cvt_pk_bf16_f32 v220, v168, v169
	v_cvt_pk_bf16_f32 v221, v170, v171
	v_cvt_pk_bf16_f32 v222, v172, v173
	v_cvt_pk_bf16_f32 v223, v174, v175
	s_andn2_b64 vcc, exec, s[6:7]
	s_waitcnt lgkmcnt(1)
	v_mfma_f32_32x32x16_bf16 v[32:47], v[212:215], v[220:223], v[32:47]
	ds_read2_b64 v[212:215], v228 offset0:68 offset1:70
	s_waitcnt lgkmcnt(1)
	v_mfma_f32_32x32x16_bf16 v[16:31], v[216:219], v[220:223], v[16:31]
	v_cvt_pk_bf16_f32 v220, v176, v177
	v_cvt_pk_bf16_f32 v221, v178, v179
	v_cvt_pk_bf16_f32 v222, v180, v181
	v_cvt_pk_bf16_f32 v223, v182, v183
	ds_read2_b64 v[216:219], v229 offset0:100 offset1:102
	s_waitcnt lgkmcnt(1)
	v_mfma_f32_32x32x16_bf16 v[32:47], v[212:215], v[220:223], v[32:47]
	ds_read2_b64 v[212:215], v228 offset0:72 offset1:74
	s_waitcnt lgkmcnt(1)
	v_mfma_f32_32x32x16_bf16 v[16:31], v[216:219], v[220:223], v[16:31]
	v_cvt_pk_bf16_f32 v220, v184, v185
	v_cvt_pk_bf16_f32 v221, v186, v187
	v_cvt_pk_bf16_f32 v222, v188, v189
	v_cvt_pk_bf16_f32 v223, v190, v191
	ds_read2_b64 v[216:219], v229 offset0:104 offset1:106
	s_waitcnt lgkmcnt(1)
	v_mfma_f32_32x32x16_bf16 v[32:47], v[212:215], v[220:223], v[32:47]
	ds_read2_b64 v[212:215], v228 offset0:76 offset1:78
	s_waitcnt lgkmcnt(1)
	v_mfma_f32_32x32x16_bf16 v[16:31], v[216:219], v[220:223], v[16:31]
	v_cvt_pk_bf16_f32 v220, v158, v159
	v_cvt_pk_bf16_f32 v221, v160, v161
	v_cvt_pk_bf16_f32 v222, v164, v165
	v_cvt_pk_bf16_f32 v223, v166, v167
	ds_read2_b64 v[216:219], v229 offset0:108 offset1:110
	s_waitcnt lgkmcnt(1)
	v_mfma_f32_32x32x16_bf16 v[32:47], v[212:215], v[220:223], v[32:47]
	s_waitcnt lgkmcnt(0)
	v_mfma_f32_32x32x16_bf16 v[16:31], v[216:219], v[220:223], v[16:31]
	s_cbranch_vccnz .LBB0_539
	ds_write_b128 v150, v[124:127]
	ds_write_b128 v151, v[128:131]
	ds_write_b128 v152, v[132:135]
	ds_write2_b64 v139, v[2:3], v[4:5] offset1:1
	ds_write2_b64 v230, v[6:7], v[8:9] offset1:1
